# weight conversion routine: dwordx4 row loads, 3 tiles in flight
# speedup vs baseline: 1.0024x; 1.0024x over previous
.Lwc0_loop:
	s_waitcnt vmcnt(8)
	v_readlane_b32 s52, v229, 8
	v_readlane_b32 s53, v229, 9
	v_readlane_b32 s32, v229, 10
	v_readlane_b32 s35, v229, 11
	ds_write_b32 v218, v138 offset:0
	ds_write_b32 v218, v139 offset:4
	ds_write_b32 v218, v140 offset:8
	ds_write_b32 v218, v141 offset:12
	ds_write_b32 v218, v142 offset:4160
	ds_write_b32 v218, v143 offset:4164
	ds_write_b32 v218, v144 offset:4168
	ds_write_b32 v218, v145 offset:4172
	ds_write_b32 v218, v146 offset:8320
	ds_write_b32 v218, v147 offset:8324
	ds_write_b32 v218, v148 offset:8328
	ds_write_b32 v218, v149 offset:8332
	ds_write_b32 v218, v150 offset:12480
	ds_write_b32 v218, v151 offset:12484
	ds_write_b32 v218, v152 offset:12488
	ds_write_b32 v218, v153 offset:12492
	v_mad_u32_u24 v224, v227, s35, v228
	s_waitcnt lgkmcnt(0)
	s_barrier
	ds_read2_b32 v[138:139], v219 offset1:65
	ds_read2_b32 v[140:141], v219 offset0:130 offset1:195
	ds_read2_b32 v[142:143], v220 offset0:4 offset1:69
	ds_read2_b32 v[144:145], v220 offset0:134 offset1:199
	ds_read2_b32 v[146:147], v221 offset1:65
	ds_read2_b32 v[148:149], v221 offset0:130 offset1:195
	ds_read2_b32 v[150:151], v222 offset0:4 offset1:69
	ds_read2_b32 v[152:153], v222 offset0:134 offset1:199
	s_add_u32 s96, s52, s32
	s_addc_u32 s97, s53, 0
	s_waitcnt lgkmcnt(0)
	s_barrier
	v_cvt_pk_bf16_f32 v138, v138, v139
	v_cvt_pk_bf16_f32 v139, v140, v141
	v_cvt_pk_bf16_f32 v140, v142, v143
	v_cvt_pk_bf16_f32 v141, v144, v145
	v_cvt_pk_bf16_f32 v146, v146, v147
	v_cvt_pk_bf16_f32 v147, v148, v149
	v_cvt_pk_bf16_f32 v148, v150, v151
	v_cvt_pk_bf16_f32 v149, v152, v153
	global_store_dwordx4 v224, v[138:141], s[52:53]
	global_store_dwordx4 v224, v[146:149], s[96:97]
	s_cmp_ge_u32 s100, s66
	s_cbranch_scc1 .Lwc0_tail0
	s_cmpk_ge_u32 s100, 0x900
	s_cbranch_scc1 .Lwc0_t3_4
	s_cmpk_ge_u32 s100, 0x380
	s_cbranch_scc1 .Lwc0_t2_4
	s_cmpk_ge_u32 s100, 0x280
	s_cbranch_scc1 .Lwc0_t1_4
	s_movk_i32 s41, 0x78
	s_sub_u32 s99, s100, 0
	s_mul_i32 s44, s99, 0x66667
	s_lshr_b32 s44, s44, 24
	s_mul_i32 s36, s44, 40
	s_sub_u32 s99, s99, s36
	s_mul_i32 s38, s44, 0xa0000
	s_lshl_b32 s36, s99, 8
	s_add_u32 s38, s38, s36
	s_add_u32 s38, s38, 0x0
	s_lshl_b32 s36, s99, 6
	s_mov_b32 s32, 0x10000
	s_mul_i32 s36, s36, 0x800
	s_lshl_b32 s44, s44, 7
	s_add_u32 s36, s36, s44
	s_add_u32 s36, s36, 0x0
	s_mov_b32 s37, 0x28000
	s_movk_i32 s44, 0x800
	s_mov_b32 s99, 0x2800
	s_branch .Lwc0_tj_4

.Lwc0_tj_4:
	s_load_dwordx2 s[2:3], s[0:1], s41
	s_add_u32 s52, s4, s36
	s_addc_u32 s53, s5, 0
	v_mad_u32_u24 v223, v225, s99, v226
	v_writelane_b32 v229, s52, 8
	v_writelane_b32 v229, s53, 9
	v_writelane_b32 v229, s32, 10
	v_writelane_b32 v229, s44, 11
	s_add_u32 s100, s100, s67
	s_waitcnt lgkmcnt(0)
	s_add_u32 s38, s2, s38
	s_addc_u32 s39, s3, 0
	global_load_dwordx4 v[138:141], v223, s[38:39]
	s_add_u32 s38, s38, s37
	s_addc_u32 s39, s39, 0
	global_load_dwordx4 v[142:145], v223, s[38:39]
	s_add_u32 s38, s38, s37
	s_addc_u32 s39, s39, 0
	global_load_dwordx4 v[146:149], v223, s[38:39]
	s_add_u32 s38, s38, s37
	s_addc_u32 s39, s39, 0
	global_load_dwordx4 v[150:153], v223, s[38:39]
	s_waitcnt vmcnt(8)
	v_readlane_b32 s52, v229, 12
	v_readlane_b32 s53, v229, 13
	v_readlane_b32 s32, v229, 14
	v_readlane_b32 s35, v229, 15
	ds_write_b32 v218, v154 offset:0
	ds_write_b32 v218, v155 offset:4
	ds_write_b32 v218, v156 offset:8
	ds_write_b32 v218, v157 offset:12
	ds_write_b32 v218, v158 offset:4160
	ds_write_b32 v218, v159 offset:4164
	ds_write_b32 v218, v160 offset:4168
	ds_write_b32 v218, v161 offset:4172
	ds_write_b32 v218, v162 offset:8320
	ds_write_b32 v218, v163 offset:8324
	ds_write_b32 v218, v164 offset:8328
	ds_write_b32 v218, v165 offset:8332
	ds_write_b32 v218, v166 offset:12480
	ds_write_b32 v218, v167 offset:12484
	ds_write_b32 v218, v168 offset:12488
	ds_write_b32 v218, v169 offset:12492
	v_mad_u32_u24 v224, v227, s35, v228
	s_waitcnt lgkmcnt(0)
	s_barrier
	ds_read2_b32 v[154:155], v219 offset1:65
	ds_read2_b32 v[156:157], v219 offset0:130 offset1:195
	ds_read2_b32 v[158:159], v220 offset0:4 offset1:69
	ds_read2_b32 v[160:161], v220 offset0:134 offset1:199
	ds_read2_b32 v[162:163], v221 offset1:65
	ds_read2_b32 v[164:165], v221 offset0:130 offset1:195
	ds_read2_b32 v[166:167], v222 offset0:4 offset1:69
	ds_read2_b32 v[168:169], v222 offset0:134 offset1:199
	s_add_u32 s96, s52, s32
	s_addc_u32 s97, s53, 0
	s_waitcnt lgkmcnt(0)
	s_barrier
	v_cvt_pk_bf16_f32 v154, v154, v155
	v_cvt_pk_bf16_f32 v155, v156, v157
	v_cvt_pk_bf16_f32 v156, v158, v159
	v_cvt_pk_bf16_f32 v157, v160, v161
	v_cvt_pk_bf16_f32 v162, v162, v163
	v_cvt_pk_bf16_f32 v163, v164, v165
	v_cvt_pk_bf16_f32 v164, v166, v167
	v_cvt_pk_bf16_f32 v165, v168, v169
	global_store_dwordx4 v224, v[154:157], s[52:53]
	global_store_dwordx4 v224, v[162:165], s[96:97]
	s_cmp_ge_u32 s100, s66
	s_cbranch_scc1 .Lwc0_tail1
	s_cmpk_ge_u32 s100, 0x900
	s_cbranch_scc1 .Lwc0_t3_5
	s_cmpk_ge_u32 s100, 0x380
	s_cbranch_scc1 .Lwc0_t2_5
	s_cmpk_ge_u32 s100, 0x280
	s_cbranch_scc1 .Lwc0_t1_5
	s_movk_i32 s41, 0x78
	s_sub_u32 s99, s100, 0
	s_mul_i32 s44, s99, 0x66667
	s_lshr_b32 s44, s44, 24
	s_mul_i32 s36, s44, 40
	s_sub_u32 s99, s99, s36
	s_mul_i32 s38, s44, 0xa0000
	s_lshl_b32 s36, s99, 8
	s_add_u32 s38, s38, s36
	s_add_u32 s38, s38, 0x0
	s_lshl_b32 s36, s99, 6
	s_mov_b32 s32, 0x10000
	s_mul_i32 s36, s36, 0x800
	s_lshl_b32 s44, s44, 7
	s_add_u32 s36, s36, s44
	s_add_u32 s36, s36, 0x0
	s_mov_b32 s37, 0x28000
	s_movk_i32 s44, 0x800
	s_mov_b32 s99, 0x2800
	s_branch .Lwc0_tj_5

.Lwc0_tj_5:
	s_load_dwordx2 s[2:3], s[0:1], s41
	s_add_u32 s52, s4, s36
	s_addc_u32 s53, s5, 0
	v_mad_u32_u24 v223, v225, s99, v226
	v_writelane_b32 v229, s52, 12
	v_writelane_b32 v229, s53, 13
	v_writelane_b32 v229, s32, 14
	v_writelane_b32 v229, s44, 15
	s_add_u32 s100, s100, s67
	s_waitcnt lgkmcnt(0)
	s_add_u32 s38, s2, s38
	s_addc_u32 s39, s3, 0
	global_load_dwordx4 v[154:157], v223, s[38:39]
	s_add_u32 s38, s38, s37
	s_addc_u32 s39, s39, 0
	global_load_dwordx4 v[158:161], v223, s[38:39]
	s_add_u32 s38, s38, s37
	s_addc_u32 s39, s39, 0
	global_load_dwordx4 v[162:165], v223, s[38:39]
	s_add_u32 s38, s38, s37
	s_addc_u32 s39, s39, 0
	global_load_dwordx4 v[166:169], v223, s[38:39]
	s_waitcnt vmcnt(8)
	v_readlane_b32 s52, v229, 16
	v_readlane_b32 s53, v229, 17
	v_readlane_b32 s32, v229, 18
	v_readlane_b32 s35, v229, 19
	ds_write_b32 v218, v170 offset:0
	ds_write_b32 v218, v171 offset:4
	ds_write_b32 v218, v172 offset:8
	ds_write_b32 v218, v173 offset:12
	ds_write_b32 v218, v174 offset:4160
	ds_write_b32 v218, v175 offset:4164
	ds_write_b32 v218, v176 offset:4168
	ds_write_b32 v218, v177 offset:4172
	ds_write_b32 v218, v178 offset:8320
	ds_write_b32 v218, v179 offset:8324
	ds_write_b32 v218, v180 offset:8328
	ds_write_b32 v218, v181 offset:8332
	ds_write_b32 v218, v182 offset:12480
	ds_write_b32 v218, v183 offset:12484
	ds_write_b32 v218, v184 offset:12488
	ds_write_b32 v218, v185 offset:12492
	v_mad_u32_u24 v224, v227, s35, v228
	s_waitcnt lgkmcnt(0)
	s_barrier
	ds_read2_b32 v[170:171], v219 offset1:65
	ds_read2_b32 v[172:173], v219 offset0:130 offset1:195
	ds_read2_b32 v[174:175], v220 offset0:4 offset1:69
	ds_read2_b32 v[176:177], v220 offset0:134 offset1:199
	ds_read2_b32 v[178:179], v221 offset1:65
	ds_read2_b32 v[180:181], v221 offset0:130 offset1:195
	ds_read2_b32 v[182:183], v222 offset0:4 offset1:69
	ds_read2_b32 v[184:185], v222 offset0:134 offset1:199
	s_add_u32 s96, s52, s32
	s_addc_u32 s97, s53, 0
	s_waitcnt lgkmcnt(0)
	s_barrier
	v_cvt_pk_bf16_f32 v170, v170, v171
	v_cvt_pk_bf16_f32 v171, v172, v173
	v_cvt_pk_bf16_f32 v172, v174, v175
	v_cvt_pk_bf16_f32 v173, v176, v177
	v_cvt_pk_bf16_f32 v178, v178, v179
	v_cvt_pk_bf16_f32 v179, v180, v181
	v_cvt_pk_bf16_f32 v180, v182, v183
	v_cvt_pk_bf16_f32 v181, v184, v185
	global_store_dwordx4 v224, v[170:173], s[52:53]
	global_store_dwordx4 v224, v[178:181], s[96:97]
	s_cmp_ge_u32 s100, s66
	s_cbranch_scc1 .Lwc0_tail2
	s_cmpk_ge_u32 s100, 0x900
	s_cbranch_scc1 .Lwc0_t3_6
	s_cmpk_ge_u32 s100, 0x380
	s_cbranch_scc1 .Lwc0_t2_6
	s_cmpk_ge_u32 s100, 0x280
	s_cbranch_scc1 .Lwc0_t1_6
	s_movk_i32 s41, 0x78
	s_sub_u32 s99, s100, 0
	s_mul_i32 s44, s99, 0x66667
	s_lshr_b32 s44, s44, 24
	s_mul_i32 s36, s44, 40
	s_sub_u32 s99, s99, s36
	s_mul_i32 s38, s44, 0xa0000
	s_lshl_b32 s36, s99, 8
	s_add_u32 s38, s38, s36
	s_add_u32 s38, s38, 0x0
	s_lshl_b32 s36, s99, 6
	s_mov_b32 s32, 0x10000
	s_mul_i32 s36, s36, 0x800
	s_lshl_b32 s44, s44, 7
	s_add_u32 s36, s36, s44
	s_add_u32 s36, s36, 0x0
	s_mov_b32 s37, 0x28000
	s_movk_i32 s44, 0x800
	s_mov_b32 s99, 0x2800
	s_branch .Lwc0_tj_6

.Lwc0_tj_6:
	s_load_dwordx2 s[2:3], s[0:1], s41
	s_add_u32 s52, s4, s36
	s_addc_u32 s53, s5, 0
	v_mad_u32_u24 v223, v225, s99, v226
	v_writelane_b32 v229, s52, 16
	v_writelane_b32 v229, s53, 17
	v_writelane_b32 v229, s32, 18
	v_writelane_b32 v229, s44, 19
	s_add_u32 s100, s100, s67
	s_waitcnt lgkmcnt(0)
	s_add_u32 s38, s2, s38
	s_addc_u32 s39, s3, 0
	global_load_dwordx4 v[170:173], v223, s[38:39]
	s_add_u32 s38, s38, s37
	s_addc_u32 s39, s39, 0
	global_load_dwordx4 v[174:177], v223, s[38:39]
	s_add_u32 s38, s38, s37
	s_addc_u32 s39, s39, 0
	global_load_dwordx4 v[178:181], v223, s[38:39]
	s_add_u32 s38, s38, s37
	s_addc_u32 s39, s39, 0
	global_load_dwordx4 v[182:185], v223, s[38:39]
	s_branch .Lwc0_loop
.Lwc0_tail0:
	s_waitcnt vmcnt(0)
	v_readlane_b32 s52, v229, 12
	v_readlane_b32 s53, v229, 13
	v_readlane_b32 s32, v229, 14
	v_readlane_b32 s35, v229, 15
	ds_write_b32 v218, v154 offset:0
	ds_write_b32 v218, v155 offset:4
	ds_write_b32 v218, v156 offset:8
	ds_write_b32 v218, v157 offset:12
	ds_write_b32 v218, v158 offset:4160
	ds_write_b32 v218, v159 offset:4164
	ds_write_b32 v218, v160 offset:4168
	ds_write_b32 v218, v161 offset:4172
	ds_write_b32 v218, v162 offset:8320
	ds_write_b32 v218, v163 offset:8324
	ds_write_b32 v218, v164 offset:8328
	ds_write_b32 v218, v165 offset:8332
	ds_write_b32 v218, v166 offset:12480
	ds_write_b32 v218, v167 offset:12484
	ds_write_b32 v218, v168 offset:12488
	ds_write_b32 v218, v169 offset:12492
	v_mad_u32_u24 v224, v227, s35, v228
	s_waitcnt lgkmcnt(0)
	s_barrier
	ds_read2_b32 v[154:155], v219 offset1:65
	ds_read2_b32 v[156:157], v219 offset0:130 offset1:195
	ds_read2_b32 v[158:159], v220 offset0:4 offset1:69
	ds_read2_b32 v[160:161], v220 offset0:134 offset1:199
	ds_read2_b32 v[162:163], v221 offset1:65
	ds_read2_b32 v[164:165], v221 offset0:130 offset1:195
	ds_read2_b32 v[166:167], v222 offset0:4 offset1:69
	ds_read2_b32 v[168:169], v222 offset0:134 offset1:199
	s_add_u32 s96, s52, s32
	s_addc_u32 s97, s53, 0
	s_waitcnt lgkmcnt(0)
	s_barrier
	v_cvt_pk_bf16_f32 v154, v154, v155
	v_cvt_pk_bf16_f32 v155, v156, v157
	v_cvt_pk_bf16_f32 v156, v158, v159
	v_cvt_pk_bf16_f32 v157, v160, v161
	v_cvt_pk_bf16_f32 v162, v162, v163
	v_cvt_pk_bf16_f32 v163, v164, v165
	v_cvt_pk_bf16_f32 v164, v166, v167
	v_cvt_pk_bf16_f32 v165, v168, v169
	global_store_dwordx4 v224, v[154:157], s[52:53]
	global_store_dwordx4 v224, v[162:165], s[96:97]
	v_readlane_b32 s52, v229, 16
	v_readlane_b32 s53, v229, 17
	v_readlane_b32 s32, v229, 18
	v_readlane_b32 s35, v229, 19
	ds_write_b32 v218, v170 offset:0
	ds_write_b32 v218, v171 offset:4
	ds_write_b32 v218, v172 offset:8
	ds_write_b32 v218, v173 offset:12
	ds_write_b32 v218, v174 offset:4160
	ds_write_b32 v218, v175 offset:4164
	ds_write_b32 v218, v176 offset:4168
	ds_write_b32 v218, v177 offset:4172
	ds_write_b32 v218, v178 offset:8320
	ds_write_b32 v218, v179 offset:8324
	ds_write_b32 v218, v180 offset:8328
	ds_write_b32 v218, v181 offset:8332
	ds_write_b32 v218, v182 offset:12480
	ds_write_b32 v218, v183 offset:12484
	ds_write_b32 v218, v184 offset:12488
	ds_write_b32 v218, v185 offset:12492
	v_mad_u32_u24 v224, v227, s35, v228
	s_waitcnt lgkmcnt(0)
	s_barrier
	ds_read2_b32 v[170:171], v219 offset1:65
	ds_read2_b32 v[172:173], v219 offset0:130 offset1:195
	ds_read2_b32 v[174:175], v220 offset0:4 offset1:69
	ds_read2_b32 v[176:177], v220 offset0:134 offset1:199
	ds_read2_b32 v[178:179], v221 offset1:65
	ds_read2_b32 v[180:181], v221 offset0:130 offset1:195
	ds_read2_b32 v[182:183], v222 offset0:4 offset1:69
	ds_read2_b32 v[184:185], v222 offset0:134 offset1:199
	s_add_u32 s96, s52, s32
	s_addc_u32 s97, s53, 0
	s_waitcnt lgkmcnt(0)
	s_barrier
	v_cvt_pk_bf16_f32 v170, v170, v171
	v_cvt_pk_bf16_f32 v171, v172, v173
	v_cvt_pk_bf16_f32 v172, v174, v175
	v_cvt_pk_bf16_f32 v173, v176, v177
	v_cvt_pk_bf16_f32 v178, v178, v179
	v_cvt_pk_bf16_f32 v179, v180, v181
	v_cvt_pk_bf16_f32 v180, v182, v183
	v_cvt_pk_bf16_f32 v181, v184, v185
	global_store_dwordx4 v224, v[170:173], s[52:53]
	global_store_dwordx4 v224, v[178:181], s[96:97]
	s_branch .Lwc0_done
.Lwc0_tail1:
	s_waitcnt vmcnt(0)
	v_readlane_b32 s52, v229, 16
	v_readlane_b32 s53, v229, 17
	v_readlane_b32 s32, v229, 18
	v_readlane_b32 s35, v229, 19
	ds_write_b32 v218, v170 offset:0
	ds_write_b32 v218, v171 offset:4
	ds_write_b32 v218, v172 offset:8
	ds_write_b32 v218, v173 offset:12
	ds_write_b32 v218, v174 offset:4160
	ds_write_b32 v218, v175 offset:4164
	ds_write_b32 v218, v176 offset:4168
	ds_write_b32 v218, v177 offset:4172
	ds_write_b32 v218, v178 offset:8320
	ds_write_b32 v218, v179 offset:8324
	ds_write_b32 v218, v180 offset:8328
	ds_write_b32 v218, v181 offset:8332
	ds_write_b32 v218, v182 offset:12480
	ds_write_b32 v218, v183 offset:12484
	ds_write_b32 v218, v184 offset:12488
	ds_write_b32 v218, v185 offset:12492
	v_mad_u32_u24 v224, v227, s35, v228
	s_waitcnt lgkmcnt(0)
	s_barrier
	ds_read2_b32 v[170:171], v219 offset1:65
	ds_read2_b32 v[172:173], v219 offset0:130 offset1:195
	ds_read2_b32 v[174:175], v220 offset0:4 offset1:69
	ds_read2_b32 v[176:177], v220 offset0:134 offset1:199
	ds_read2_b32 v[178:179], v221 offset1:65
	ds_read2_b32 v[180:181], v221 offset0:130 offset1:195
	ds_read2_b32 v[182:183], v222 offset0:4 offset1:69
	ds_read2_b32 v[184:185], v222 offset0:134 offset1:199
	s_add_u32 s96, s52, s32
	s_addc_u32 s97, s53, 0
	s_waitcnt lgkmcnt(0)
	s_barrier
	v_cvt_pk_bf16_f32 v170, v170, v171
	v_cvt_pk_bf16_f32 v171, v172, v173
	v_cvt_pk_bf16_f32 v172, v174, v175
	v_cvt_pk_bf16_f32 v173, v176, v177
	v_cvt_pk_bf16_f32 v178, v178, v179
	v_cvt_pk_bf16_f32 v179, v180, v181
	v_cvt_pk_bf16_f32 v180, v182, v183
	v_cvt_pk_bf16_f32 v181, v184, v185
	global_store_dwordx4 v224, v[170:173], s[52:53]
	global_store_dwordx4 v224, v[178:181], s[96:97]
	v_readlane_b32 s52, v229, 8
	v_readlane_b32 s53, v229, 9
	v_readlane_b32 s32, v229, 10
	v_readlane_b32 s35, v229, 11
	ds_write_b32 v218, v138 offset:0
	ds_write_b32 v218, v139 offset:4
	ds_write_b32 v218, v140 offset:8
	ds_write_b32 v218, v141 offset:12
	ds_write_b32 v218, v142 offset:4160
	ds_write_b32 v218, v143 offset:4164
	ds_write_b32 v218, v144 offset:4168
	ds_write_b32 v218, v145 offset:4172
	ds_write_b32 v218, v146 offset:8320
	ds_write_b32 v218, v147 offset:8324
	ds_write_b32 v218, v148 offset:8328
	ds_write_b32 v218, v149 offset:8332
	ds_write_b32 v218, v150 offset:12480
	ds_write_b32 v218, v151 offset:12484
	ds_write_b32 v218, v152 offset:12488
	ds_write_b32 v218, v153 offset:12492
	v_mad_u32_u24 v224, v227, s35, v228
	s_waitcnt lgkmcnt(0)
	s_barrier
	ds_read2_b32 v[138:139], v219 offset1:65
	ds_read2_b32 v[140:141], v219 offset0:130 offset1:195
	ds_read2_b32 v[142:143], v220 offset0:4 offset1:69
	ds_read2_b32 v[144:145], v220 offset0:134 offset1:199
	ds_read2_b32 v[146:147], v221 offset1:65
	ds_read2_b32 v[148:149], v221 offset0:130 offset1:195
	ds_read2_b32 v[150:151], v222 offset0:4 offset1:69
	ds_read2_b32 v[152:153], v222 offset0:134 offset1:199
	s_add_u32 s96, s52, s32
	s_addc_u32 s97, s53, 0
	s_waitcnt lgkmcnt(0)
	s_barrier
	v_cvt_pk_bf16_f32 v138, v138, v139
	v_cvt_pk_bf16_f32 v139, v140, v141
	v_cvt_pk_bf16_f32 v140, v142, v143
	v_cvt_pk_bf16_f32 v141, v144, v145
	v_cvt_pk_bf16_f32 v146, v146, v147
	v_cvt_pk_bf16_f32 v147, v148, v149
	v_cvt_pk_bf16_f32 v148, v150, v151
	v_cvt_pk_bf16_f32 v149, v152, v153
	global_store_dwordx4 v224, v[138:141], s[52:53]
	global_store_dwordx4 v224, v[146:149], s[96:97]
	s_branch .Lwc0_done
.Lwc0_tail2:
	s_waitcnt vmcnt(0)
	v_readlane_b32 s52, v229, 8
	v_readlane_b32 s53, v229, 9
	v_readlane_b32 s32, v229, 10
	v_readlane_b32 s35, v229, 11
	ds_write_b32 v218, v138 offset:0
	ds_write_b32 v218, v139 offset:4
	ds_write_b32 v218, v140 offset:8
	ds_write_b32 v218, v141 offset:12
	ds_write_b32 v218, v142 offset:4160
	ds_write_b32 v218, v143 offset:4164
	ds_write_b32 v218, v144 offset:4168
	ds_write_b32 v218, v145 offset:4172
	ds_write_b32 v218, v146 offset:8320
	ds_write_b32 v218, v147 offset:8324
	ds_write_b32 v218, v148 offset:8328
	ds_write_b32 v218, v149 offset:8332
	ds_write_b32 v218, v150 offset:12480
	ds_write_b32 v218, v151 offset:12484
	ds_write_b32 v218, v152 offset:12488
	ds_write_b32 v218, v153 offset:12492
	v_mad_u32_u24 v224, v227, s35, v228
	s_waitcnt lgkmcnt(0)
	s_barrier
	ds_read2_b32 v[138:139], v219 offset1:65
	ds_read2_b32 v[140:141], v219 offset0:130 offset1:195
	ds_read2_b32 v[142:143], v220 offset0:4 offset1:69
	ds_read2_b32 v[144:145], v220 offset0:134 offset1:199
	ds_read2_b32 v[146:147], v221 offset1:65
	ds_read2_b32 v[148:149], v221 offset0:130 offset1:195
	ds_read2_b32 v[150:151], v222 offset0:4 offset1:69
	ds_read2_b32 v[152:153], v222 offset0:134 offset1:199
	s_add_u32 s96, s52, s32
	s_addc_u32 s97, s53, 0
	s_waitcnt lgkmcnt(0)
	s_barrier
	v_cvt_pk_bf16_f32 v138, v138, v139
	v_cvt_pk_bf16_f32 v139, v140, v141
	v_cvt_pk_bf16_f32 v140, v142, v143
	v_cvt_pk_bf16_f32 v141, v144, v145
	v_cvt_pk_bf16_f32 v146, v146, v147
	v_cvt_pk_bf16_f32 v147, v148, v149
	v_cvt_pk_bf16_f32 v148, v150, v151
	v_cvt_pk_bf16_f32 v149, v152, v153
	global_store_dwordx4 v224, v[138:141], s[52:53]
	global_store_dwordx4 v224, v[146:149], s[96:97]
	v_readlane_b32 s52, v229, 12
	v_readlane_b32 s53, v229, 13
	v_readlane_b32 s32, v229, 14
	v_readlane_b32 s35, v229, 15
	ds_write_b32 v218, v154 offset:0
	ds_write_b32 v218, v155 offset:4
	ds_write_b32 v218, v156 offset:8
	ds_write_b32 v218, v157 offset:12
	ds_write_b32 v218, v158 offset:4160
	ds_write_b32 v218, v159 offset:4164
	ds_write_b32 v218, v160 offset:4168
	ds_write_b32 v218, v161 offset:4172
	ds_write_b32 v218, v162 offset:8320
	ds_write_b32 v218, v163 offset:8324
	ds_write_b32 v218, v164 offset:8328
	ds_write_b32 v218, v165 offset:8332
	ds_write_b32 v218, v166 offset:12480
	ds_write_b32 v218, v167 offset:12484
	ds_write_b32 v218, v168 offset:12488
	ds_write_b32 v218, v169 offset:12492
	v_mad_u32_u24 v224, v227, s35, v228
	s_waitcnt lgkmcnt(0)
	s_barrier
	ds_read2_b32 v[154:155], v219 offset1:65
	ds_read2_b32 v[156:157], v219 offset0:130 offset1:195
	ds_read2_b32 v[158:159], v220 offset0:4 offset1:69
	ds_read2_b32 v[160:161], v220 offset0:134 offset1:199
	ds_read2_b32 v[162:163], v221 offset1:65
	ds_read2_b32 v[164:165], v221 offset0:130 offset1:195
	ds_read2_b32 v[166:167], v222 offset0:4 offset1:69
	ds_read2_b32 v[168:169], v222 offset0:134 offset1:199
	s_add_u32 s96, s52, s32
	s_addc_u32 s97, s53, 0
	s_waitcnt lgkmcnt(0)
	s_barrier
	v_cvt_pk_bf16_f32 v154, v154, v155
	v_cvt_pk_bf16_f32 v155, v156, v157
	v_cvt_pk_bf16_f32 v156, v158, v159
	v_cvt_pk_bf16_f32 v157, v160, v161
	v_cvt_pk_bf16_f32 v162, v162, v163
	v_cvt_pk_bf16_f32 v163, v164, v165
	v_cvt_pk_bf16_f32 v164, v166, v167
	v_cvt_pk_bf16_f32 v165, v168, v169
	global_store_dwordx4 v224, v[154:157], s[52:53]
	global_store_dwordx4 v224, v[162:165], s[96:97]
	s_branch .Lwc0_done
.Lwc0_p2:
	s_waitcnt vmcnt(0)
	v_readlane_b32 s52, v229, 8
	v_readlane_b32 s53, v229, 9
	v_readlane_b32 s32, v229, 10
	v_readlane_b32 s35, v229, 11
	ds_write_b32 v218, v138 offset:0
	ds_write_b32 v218, v139 offset:4
	ds_write_b32 v218, v140 offset:8
	ds_write_b32 v218, v141 offset:12
	ds_write_b32 v218, v142 offset:4160
	ds_write_b32 v218, v143 offset:4164
	ds_write_b32 v218, v144 offset:4168
	ds_write_b32 v218, v145 offset:4172
	ds_write_b32 v218, v146 offset:8320
	ds_write_b32 v218, v147 offset:8324
	ds_write_b32 v218, v148 offset:8328
	ds_write_b32 v218, v149 offset:8332
	ds_write_b32 v218, v150 offset:12480
	ds_write_b32 v218, v151 offset:12484
	ds_write_b32 v218, v152 offset:12488
	ds_write_b32 v218, v153 offset:12492
	v_mad_u32_u24 v224, v227, s35, v228
	s_waitcnt lgkmcnt(0)
	s_barrier
	ds_read2_b32 v[138:139], v219 offset1:65
	ds_read2_b32 v[140:141], v219 offset0:130 offset1:195
	ds_read2_b32 v[142:143], v220 offset0:4 offset1:69
	ds_read2_b32 v[144:145], v220 offset0:134 offset1:199
	ds_read2_b32 v[146:147], v221 offset1:65
	ds_read2_b32 v[148:149], v221 offset0:130 offset1:195
	ds_read2_b32 v[150:151], v222 offset0:4 offset1:69
	ds_read2_b32 v[152:153], v222 offset0:134 offset1:199
	s_add_u32 s96, s52, s32
	s_addc_u32 s97, s53, 0
	s_waitcnt lgkmcnt(0)
	s_barrier
	v_cvt_pk_bf16_f32 v138, v138, v139
	v_cvt_pk_bf16_f32 v139, v140, v141
	v_cvt_pk_bf16_f32 v140, v142, v143
	v_cvt_pk_bf16_f32 v141, v144, v145
	v_cvt_pk_bf16_f32 v146, v146, v147
	v_cvt_pk_bf16_f32 v147, v148, v149
	v_cvt_pk_bf16_f32 v148, v150, v151
	v_cvt_pk_bf16_f32 v149, v152, v153
	global_store_dwordx4 v224, v[138:141], s[52:53]
	global_store_dwordx4 v224, v[146:149], s[96:97]
	v_readlane_b32 s52, v229, 12
	v_readlane_b32 s53, v229, 13
	v_readlane_b32 s32, v229, 14
	v_readlane_b32 s35, v229, 15
	ds_write_b32 v218, v154 offset:0
	ds_write_b32 v218, v155 offset:4
	ds_write_b32 v218, v156 offset:8
	ds_write_b32 v218, v157 offset:12
	ds_write_b32 v218, v158 offset:4160
	ds_write_b32 v218, v159 offset:4164
	ds_write_b32 v218, v160 offset:4168
	ds_write_b32 v218, v161 offset:4172
	ds_write_b32 v218, v162 offset:8320
	ds_write_b32 v218, v163 offset:8324
	ds_write_b32 v218, v164 offset:8328
	ds_write_b32 v218, v165 offset:8332
	ds_write_b32 v218, v166 offset:12480
	ds_write_b32 v218, v167 offset:12484
	ds_write_b32 v218, v168 offset:12488
	ds_write_b32 v218, v169 offset:12492
	v_mad_u32_u24 v224, v227, s35, v228
	s_waitcnt lgkmcnt(0)
	s_barrier
	ds_read2_b32 v[154:155], v219 offset1:65
	ds_read2_b32 v[156:157], v219 offset0:130 offset1:195
	ds_read2_b32 v[158:159], v220 offset0:4 offset1:69
	ds_read2_b32 v[160:161], v220 offset0:134 offset1:199
	ds_read2_b32 v[162:163], v221 offset1:65
	ds_read2_b32 v[164:165], v221 offset0:130 offset1:195
	ds_read2_b32 v[166:167], v222 offset0:4 offset1:69
	ds_read2_b32 v[168:169], v222 offset0:134 offset1:199
	s_add_u32 s96, s52, s32
	s_addc_u32 s97, s53, 0
	s_waitcnt lgkmcnt(0)
	s_barrier
	v_cvt_pk_bf16_f32 v154, v154, v155
	v_cvt_pk_bf16_f32 v155, v156, v157
	v_cvt_pk_bf16_f32 v156, v158, v159
	v_cvt_pk_bf16_f32 v157, v160, v161
	v_cvt_pk_bf16_f32 v162, v162, v163
	v_cvt_pk_bf16_f32 v163, v164, v165
	v_cvt_pk_bf16_f32 v164, v166, v167
	v_cvt_pk_bf16_f32 v165, v168, v169
	global_store_dwordx4 v224, v[154:157], s[52:53]
	global_store_dwordx4 v224, v[162:165], s[96:97]
	s_branch .Lwc0_done

.Lwcm0_loop:
	s_waitcnt vmcnt(8)
	v_readlane_b32 s20, v237, 8
	v_readlane_b32 s21, v237, 9
	v_readlane_b32 s32, v237, 10
	v_readlane_b32 s35, v237, 11
	ds_write_b32 v226, v146 offset:0
	ds_write_b32 v226, v147 offset:4
	ds_write_b32 v226, v148 offset:8
	ds_write_b32 v226, v149 offset:12
	ds_write_b32 v226, v150 offset:4160
	ds_write_b32 v226, v151 offset:4164
	ds_write_b32 v226, v152 offset:4168
	ds_write_b32 v226, v153 offset:4172
	ds_write_b32 v226, v154 offset:8320
	ds_write_b32 v226, v155 offset:8324
	ds_write_b32 v226, v156 offset:8328
	ds_write_b32 v226, v157 offset:8332
	ds_write_b32 v226, v158 offset:12480
	ds_write_b32 v226, v159 offset:12484
	ds_write_b32 v226, v160 offset:12488
	ds_write_b32 v226, v161 offset:12492
	v_mad_u32_u24 v232, v235, s35, v236
	s_waitcnt lgkmcnt(0)
	s_barrier
	ds_read2_b32 v[146:147], v227 offset1:65
	ds_read2_b32 v[148:149], v227 offset0:130 offset1:195
	ds_read2_b32 v[150:151], v228 offset0:4 offset1:69
	ds_read2_b32 v[152:153], v228 offset0:134 offset1:199
	ds_read2_b32 v[154:155], v229 offset1:65
	ds_read2_b32 v[156:157], v229 offset0:130 offset1:195
	ds_read2_b32 v[158:159], v230 offset0:4 offset1:69
	ds_read2_b32 v[160:161], v230 offset0:134 offset1:199
	s_add_u32 s26, s20, s32
	s_addc_u32 s27, s21, 0
	s_waitcnt lgkmcnt(0)
	s_barrier
	v_cvt_pk_bf16_f32 v146, v146, v147
	v_cvt_pk_bf16_f32 v147, v148, v149
	v_cvt_pk_bf16_f32 v148, v150, v151
	v_cvt_pk_bf16_f32 v149, v152, v153
	v_cvt_pk_bf16_f32 v154, v154, v155
	v_cvt_pk_bf16_f32 v155, v156, v157
	v_cvt_pk_bf16_f32 v156, v158, v159
	v_cvt_pk_bf16_f32 v157, v160, v161
	global_store_dwordx4 v232, v[146:149], s[20:21]
	global_store_dwordx4 v232, v[154:157], s[26:27]
	s_cmp_ge_u32 s100, s22
	s_cbranch_scc1 .Lwcm0_tail0
	s_cmpk_ge_u32 s100, 0x900
	s_cbranch_scc1 .Lwcm0_t3_4
	s_cmpk_ge_u32 s100, 0x380
	s_cbranch_scc1 .Lwcm0_t2_4
	s_cmpk_ge_u32 s100, 0x280
	s_cbranch_scc1 .Lwcm0_t1_4
	s_movk_i32 s14, 0x78
	s_sub_u32 s99, s100, 0
	s_mul_i32 s44, s99, 0x66667
	s_lshr_b32 s44, s44, 24
	s_mul_i32 s36, s44, 40
	s_sub_u32 s99, s99, s36
	s_mul_i32 s38, s44, 0xa0000
	s_lshl_b32 s36, s99, 8
	s_add_u32 s38, s38, s36
	s_add_u32 s38, s38, 0x0
	s_lshl_b32 s36, s99, 6
	s_mov_b32 s32, 0x10000
	s_mul_i32 s36, s36, 0x800
	s_lshl_b32 s44, s44, 7
	s_add_u32 s36, s36, s44
	s_add_u32 s36, s36, 0x0
	s_mov_b32 s37, 0x28000
	s_movk_i32 s44, 0x800
	s_mov_b32 s99, 0x2800
	s_branch .Lwcm0_tj_4

.Lwcm0_tj_4:
	s_load_dwordx2 s[8:9], s[0:1], s14
	s_add_u32 s20, s12, s36
	s_addc_u32 s21, s13, 0
	v_mad_u32_u24 v231, v233, s99, v234
	v_writelane_b32 v237, s20, 8
	v_writelane_b32 v237, s21, 9
	v_writelane_b32 v237, s32, 10
	v_writelane_b32 v237, s44, 11
	s_add_u32 s100, s100, s23
	s_waitcnt lgkmcnt(0)
	s_add_u32 s38, s8, s38
	s_addc_u32 s39, s9, 0
	global_load_dwordx4 v[146:149], v231, s[38:39]
	s_add_u32 s38, s38, s37
	s_addc_u32 s39, s39, 0
	global_load_dwordx4 v[150:153], v231, s[38:39]
	s_add_u32 s38, s38, s37
	s_addc_u32 s39, s39, 0
	global_load_dwordx4 v[154:157], v231, s[38:39]
	s_add_u32 s38, s38, s37
	s_addc_u32 s39, s39, 0
	global_load_dwordx4 v[158:161], v231, s[38:39]
	s_waitcnt vmcnt(8)
	v_readlane_b32 s20, v237, 12
	v_readlane_b32 s21, v237, 13
	v_readlane_b32 s32, v237, 14
	v_readlane_b32 s35, v237, 15
	ds_write_b32 v226, v162 offset:0
	ds_write_b32 v226, v163 offset:4
	ds_write_b32 v226, v164 offset:8
	ds_write_b32 v226, v165 offset:12
	ds_write_b32 v226, v166 offset:4160
	ds_write_b32 v226, v167 offset:4164
	ds_write_b32 v226, v168 offset:4168
	ds_write_b32 v226, v169 offset:4172
	ds_write_b32 v226, v170 offset:8320
	ds_write_b32 v226, v171 offset:8324
	ds_write_b32 v226, v172 offset:8328
	ds_write_b32 v226, v173 offset:8332
	ds_write_b32 v226, v174 offset:12480
	ds_write_b32 v226, v175 offset:12484
	ds_write_b32 v226, v176 offset:12488
	ds_write_b32 v226, v177 offset:12492
	v_mad_u32_u24 v232, v235, s35, v236
	s_waitcnt lgkmcnt(0)
	s_barrier
	ds_read2_b32 v[162:163], v227 offset1:65
	ds_read2_b32 v[164:165], v227 offset0:130 offset1:195
	ds_read2_b32 v[166:167], v228 offset0:4 offset1:69
	ds_read2_b32 v[168:169], v228 offset0:134 offset1:199
	ds_read2_b32 v[170:171], v229 offset1:65
	ds_read2_b32 v[172:173], v229 offset0:130 offset1:195
	ds_read2_b32 v[174:175], v230 offset0:4 offset1:69
	ds_read2_b32 v[176:177], v230 offset0:134 offset1:199
	s_add_u32 s26, s20, s32
	s_addc_u32 s27, s21, 0
	s_waitcnt lgkmcnt(0)
	s_barrier
	v_cvt_pk_bf16_f32 v162, v162, v163
	v_cvt_pk_bf16_f32 v163, v164, v165
	v_cvt_pk_bf16_f32 v164, v166, v167
	v_cvt_pk_bf16_f32 v165, v168, v169
	v_cvt_pk_bf16_f32 v170, v170, v171
	v_cvt_pk_bf16_f32 v171, v172, v173
	v_cvt_pk_bf16_f32 v172, v174, v175
	v_cvt_pk_bf16_f32 v173, v176, v177
	global_store_dwordx4 v232, v[162:165], s[20:21]
	global_store_dwordx4 v232, v[170:173], s[26:27]
	s_cmp_ge_u32 s100, s22
	s_cbranch_scc1 .Lwcm0_tail1
	s_cmpk_ge_u32 s100, 0x900
	s_cbranch_scc1 .Lwcm0_t3_5
	s_cmpk_ge_u32 s100, 0x380
	s_cbranch_scc1 .Lwcm0_t2_5
	s_cmpk_ge_u32 s100, 0x280
	s_cbranch_scc1 .Lwcm0_t1_5
	s_movk_i32 s14, 0x78
	s_sub_u32 s99, s100, 0
	s_mul_i32 s44, s99, 0x66667
	s_lshr_b32 s44, s44, 24
	s_mul_i32 s36, s44, 40
	s_sub_u32 s99, s99, s36
	s_mul_i32 s38, s44, 0xa0000
	s_lshl_b32 s36, s99, 8
	s_add_u32 s38, s38, s36
	s_add_u32 s38, s38, 0x0
	s_lshl_b32 s36, s99, 6
	s_mov_b32 s32, 0x10000
	s_mul_i32 s36, s36, 0x800
	s_lshl_b32 s44, s44, 7
	s_add_u32 s36, s36, s44
	s_add_u32 s36, s36, 0x0
	s_mov_b32 s37, 0x28000
	s_movk_i32 s44, 0x800
	s_mov_b32 s99, 0x2800
	s_branch .Lwcm0_tj_5

.Lwcm0_tj_5:
	s_load_dwordx2 s[8:9], s[0:1], s14
	s_add_u32 s20, s12, s36
	s_addc_u32 s21, s13, 0
	v_mad_u32_u24 v231, v233, s99, v234
	v_writelane_b32 v237, s20, 12
	v_writelane_b32 v237, s21, 13
	v_writelane_b32 v237, s32, 14
	v_writelane_b32 v237, s44, 15
	s_add_u32 s100, s100, s23
	s_waitcnt lgkmcnt(0)
	s_add_u32 s38, s8, s38
	s_addc_u32 s39, s9, 0
	global_load_dwordx4 v[162:165], v231, s[38:39]
	s_add_u32 s38, s38, s37
	s_addc_u32 s39, s39, 0
	global_load_dwordx4 v[166:169], v231, s[38:39]
	s_add_u32 s38, s38, s37
	s_addc_u32 s39, s39, 0
	global_load_dwordx4 v[170:173], v231, s[38:39]
	s_add_u32 s38, s38, s37
	s_addc_u32 s39, s39, 0
	global_load_dwordx4 v[174:177], v231, s[38:39]
	s_waitcnt vmcnt(8)
	v_readlane_b32 s20, v237, 16
	v_readlane_b32 s21, v237, 17
	v_readlane_b32 s32, v237, 18
	v_readlane_b32 s35, v237, 19
	ds_write_b32 v226, v178 offset:0
	ds_write_b32 v226, v179 offset:4
	ds_write_b32 v226, v180 offset:8
	ds_write_b32 v226, v181 offset:12
	ds_write_b32 v226, v182 offset:4160
	ds_write_b32 v226, v183 offset:4164
	ds_write_b32 v226, v184 offset:4168
	ds_write_b32 v226, v185 offset:4172
	ds_write_b32 v226, v186 offset:8320
	ds_write_b32 v226, v187 offset:8324
	ds_write_b32 v226, v188 offset:8328
	ds_write_b32 v226, v189 offset:8332
	ds_write_b32 v226, v190 offset:12480
	ds_write_b32 v226, v191 offset:12484
	ds_write_b32 v226, v192 offset:12488
	ds_write_b32 v226, v193 offset:12492
	v_mad_u32_u24 v232, v235, s35, v236
	s_waitcnt lgkmcnt(0)
	s_barrier
	ds_read2_b32 v[178:179], v227 offset1:65
	ds_read2_b32 v[180:181], v227 offset0:130 offset1:195
	ds_read2_b32 v[182:183], v228 offset0:4 offset1:69
	ds_read2_b32 v[184:185], v228 offset0:134 offset1:199
	ds_read2_b32 v[186:187], v229 offset1:65
	ds_read2_b32 v[188:189], v229 offset0:130 offset1:195
	ds_read2_b32 v[190:191], v230 offset0:4 offset1:69
	ds_read2_b32 v[192:193], v230 offset0:134 offset1:199
	s_add_u32 s26, s20, s32
	s_addc_u32 s27, s21, 0
	s_waitcnt lgkmcnt(0)
	s_barrier
	v_cvt_pk_bf16_f32 v178, v178, v179
	v_cvt_pk_bf16_f32 v179, v180, v181
	v_cvt_pk_bf16_f32 v180, v182, v183
	v_cvt_pk_bf16_f32 v181, v184, v185
	v_cvt_pk_bf16_f32 v186, v186, v187
	v_cvt_pk_bf16_f32 v187, v188, v189
	v_cvt_pk_bf16_f32 v188, v190, v191
	v_cvt_pk_bf16_f32 v189, v192, v193
	global_store_dwordx4 v232, v[178:181], s[20:21]
	global_store_dwordx4 v232, v[186:189], s[26:27]
	s_cmp_ge_u32 s100, s22
	s_cbranch_scc1 .Lwcm0_tail2
	s_cmpk_ge_u32 s100, 0x900
	s_cbranch_scc1 .Lwcm0_t3_6
	s_cmpk_ge_u32 s100, 0x380
	s_cbranch_scc1 .Lwcm0_t2_6
	s_cmpk_ge_u32 s100, 0x280
	s_cbranch_scc1 .Lwcm0_t1_6
	s_movk_i32 s14, 0x78
	s_sub_u32 s99, s100, 0
	s_mul_i32 s44, s99, 0x66667
	s_lshr_b32 s44, s44, 24
	s_mul_i32 s36, s44, 40
	s_sub_u32 s99, s99, s36
	s_mul_i32 s38, s44, 0xa0000
	s_lshl_b32 s36, s99, 8
	s_add_u32 s38, s38, s36
	s_add_u32 s38, s38, 0x0
	s_lshl_b32 s36, s99, 6
	s_mov_b32 s32, 0x10000
	s_mul_i32 s36, s36, 0x800
	s_lshl_b32 s44, s44, 7
	s_add_u32 s36, s36, s44
	s_add_u32 s36, s36, 0x0
	s_mov_b32 s37, 0x28000
	s_movk_i32 s44, 0x800
	s_mov_b32 s99, 0x2800
	s_branch .Lwcm0_tj_6

.Lwcm0_tj_6:
	s_load_dwordx2 s[8:9], s[0:1], s14
	s_add_u32 s20, s12, s36
	s_addc_u32 s21, s13, 0
	v_mad_u32_u24 v231, v233, s99, v234
	v_writelane_b32 v237, s20, 16
	v_writelane_b32 v237, s21, 17
	v_writelane_b32 v237, s32, 18
	v_writelane_b32 v237, s44, 19
	s_add_u32 s100, s100, s23
	s_waitcnt lgkmcnt(0)
	s_add_u32 s38, s8, s38
	s_addc_u32 s39, s9, 0
	global_load_dwordx4 v[178:181], v231, s[38:39]
	s_add_u32 s38, s38, s37
	s_addc_u32 s39, s39, 0
	global_load_dwordx4 v[182:185], v231, s[38:39]
	s_add_u32 s38, s38, s37
	s_addc_u32 s39, s39, 0
	global_load_dwordx4 v[186:189], v231, s[38:39]
	s_add_u32 s38, s38, s37
	s_addc_u32 s39, s39, 0
	global_load_dwordx4 v[190:193], v231, s[38:39]
	s_branch .Lwcm0_loop
.Lwcm0_tail0:
	s_waitcnt vmcnt(0)
	v_readlane_b32 s20, v237, 12
	v_readlane_b32 s21, v237, 13
	v_readlane_b32 s32, v237, 14
	v_readlane_b32 s35, v237, 15
	ds_write_b32 v226, v162 offset:0
	ds_write_b32 v226, v163 offset:4
	ds_write_b32 v226, v164 offset:8
	ds_write_b32 v226, v165 offset:12
	ds_write_b32 v226, v166 offset:4160
	ds_write_b32 v226, v167 offset:4164
	ds_write_b32 v226, v168 offset:4168
	ds_write_b32 v226, v169 offset:4172
	ds_write_b32 v226, v170 offset:8320
	ds_write_b32 v226, v171 offset:8324
	ds_write_b32 v226, v172 offset:8328
	ds_write_b32 v226, v173 offset:8332
	ds_write_b32 v226, v174 offset:12480
	ds_write_b32 v226, v175 offset:12484
	ds_write_b32 v226, v176 offset:12488
	ds_write_b32 v226, v177 offset:12492
	v_mad_u32_u24 v232, v235, s35, v236
	s_waitcnt lgkmcnt(0)
	s_barrier
	ds_read2_b32 v[162:163], v227 offset1:65
	ds_read2_b32 v[164:165], v227 offset0:130 offset1:195
	ds_read2_b32 v[166:167], v228 offset0:4 offset1:69
	ds_read2_b32 v[168:169], v228 offset0:134 offset1:199
	ds_read2_b32 v[170:171], v229 offset1:65
	ds_read2_b32 v[172:173], v229 offset0:130 offset1:195
	ds_read2_b32 v[174:175], v230 offset0:4 offset1:69
	ds_read2_b32 v[176:177], v230 offset0:134 offset1:199
	s_add_u32 s26, s20, s32
	s_addc_u32 s27, s21, 0
	s_waitcnt lgkmcnt(0)
	s_barrier
	v_cvt_pk_bf16_f32 v162, v162, v163
	v_cvt_pk_bf16_f32 v163, v164, v165
	v_cvt_pk_bf16_f32 v164, v166, v167
	v_cvt_pk_bf16_f32 v165, v168, v169
	v_cvt_pk_bf16_f32 v170, v170, v171
	v_cvt_pk_bf16_f32 v171, v172, v173
	v_cvt_pk_bf16_f32 v172, v174, v175
	v_cvt_pk_bf16_f32 v173, v176, v177
	global_store_dwordx4 v232, v[162:165], s[20:21]
	global_store_dwordx4 v232, v[170:173], s[26:27]
	v_readlane_b32 s20, v237, 16
	v_readlane_b32 s21, v237, 17
	v_readlane_b32 s32, v237, 18
	v_readlane_b32 s35, v237, 19
	ds_write_b32 v226, v178 offset:0
	ds_write_b32 v226, v179 offset:4
	ds_write_b32 v226, v180 offset:8
	ds_write_b32 v226, v181 offset:12
	ds_write_b32 v226, v182 offset:4160
	ds_write_b32 v226, v183 offset:4164
	ds_write_b32 v226, v184 offset:4168
	ds_write_b32 v226, v185 offset:4172
	ds_write_b32 v226, v186 offset:8320
	ds_write_b32 v226, v187 offset:8324
	ds_write_b32 v226, v188 offset:8328
	ds_write_b32 v226, v189 offset:8332
	ds_write_b32 v226, v190 offset:12480
	ds_write_b32 v226, v191 offset:12484
	ds_write_b32 v226, v192 offset:12488
	ds_write_b32 v226, v193 offset:12492
	v_mad_u32_u24 v232, v235, s35, v236
	s_waitcnt lgkmcnt(0)
	s_barrier
	ds_read2_b32 v[178:179], v227 offset1:65
	ds_read2_b32 v[180:181], v227 offset0:130 offset1:195
	ds_read2_b32 v[182:183], v228 offset0:4 offset1:69
	ds_read2_b32 v[184:185], v228 offset0:134 offset1:199
	ds_read2_b32 v[186:187], v229 offset1:65
	ds_read2_b32 v[188:189], v229 offset0:130 offset1:195
	ds_read2_b32 v[190:191], v230 offset0:4 offset1:69
	ds_read2_b32 v[192:193], v230 offset0:134 offset1:199
	s_add_u32 s26, s20, s32
	s_addc_u32 s27, s21, 0
	s_waitcnt lgkmcnt(0)
	s_barrier
	v_cvt_pk_bf16_f32 v178, v178, v179
	v_cvt_pk_bf16_f32 v179, v180, v181
	v_cvt_pk_bf16_f32 v180, v182, v183
	v_cvt_pk_bf16_f32 v181, v184, v185
	v_cvt_pk_bf16_f32 v186, v186, v187
	v_cvt_pk_bf16_f32 v187, v188, v189
	v_cvt_pk_bf16_f32 v188, v190, v191
	v_cvt_pk_bf16_f32 v189, v192, v193
	global_store_dwordx4 v232, v[178:181], s[20:21]
	global_store_dwordx4 v232, v[186:189], s[26:27]
	s_branch .Lwcm0_done
.Lwcm0_tail1:
	s_waitcnt vmcnt(0)
	v_readlane_b32 s20, v237, 16
	v_readlane_b32 s21, v237, 17
	v_readlane_b32 s32, v237, 18
	v_readlane_b32 s35, v237, 19
	ds_write_b32 v226, v178 offset:0
	ds_write_b32 v226, v179 offset:4
	ds_write_b32 v226, v180 offset:8
	ds_write_b32 v226, v181 offset:12
	ds_write_b32 v226, v182 offset:4160
	ds_write_b32 v226, v183 offset:4164
	ds_write_b32 v226, v184 offset:4168
	ds_write_b32 v226, v185 offset:4172
	ds_write_b32 v226, v186 offset:8320
	ds_write_b32 v226, v187 offset:8324
	ds_write_b32 v226, v188 offset:8328
	ds_write_b32 v226, v189 offset:8332
	ds_write_b32 v226, v190 offset:12480
	ds_write_b32 v226, v191 offset:12484
	ds_write_b32 v226, v192 offset:12488
	ds_write_b32 v226, v193 offset:12492
	v_mad_u32_u24 v232, v235, s35, v236
	s_waitcnt lgkmcnt(0)
	s_barrier
	ds_read2_b32 v[178:179], v227 offset1:65
	ds_read2_b32 v[180:181], v227 offset0:130 offset1:195
	ds_read2_b32 v[182:183], v228 offset0:4 offset1:69
	ds_read2_b32 v[184:185], v228 offset0:134 offset1:199
	ds_read2_b32 v[186:187], v229 offset1:65
	ds_read2_b32 v[188:189], v229 offset0:130 offset1:195
	ds_read2_b32 v[190:191], v230 offset0:4 offset1:69
	ds_read2_b32 v[192:193], v230 offset0:134 offset1:199
	s_add_u32 s26, s20, s32
	s_addc_u32 s27, s21, 0
	s_waitcnt lgkmcnt(0)
	s_barrier
	v_cvt_pk_bf16_f32 v178, v178, v179
	v_cvt_pk_bf16_f32 v179, v180, v181
	v_cvt_pk_bf16_f32 v180, v182, v183
	v_cvt_pk_bf16_f32 v181, v184, v185
	v_cvt_pk_bf16_f32 v186, v186, v187
	v_cvt_pk_bf16_f32 v187, v188, v189
	v_cvt_pk_bf16_f32 v188, v190, v191
	v_cvt_pk_bf16_f32 v189, v192, v193
	global_store_dwordx4 v232, v[178:181], s[20:21]
	global_store_dwordx4 v232, v[186:189], s[26:27]
	v_readlane_b32 s20, v237, 8
	v_readlane_b32 s21, v237, 9
	v_readlane_b32 s32, v237, 10
	v_readlane_b32 s35, v237, 11
	ds_write_b32 v226, v146 offset:0
	ds_write_b32 v226, v147 offset:4
	ds_write_b32 v226, v148 offset:8
	ds_write_b32 v226, v149 offset:12
	ds_write_b32 v226, v150 offset:4160
	ds_write_b32 v226, v151 offset:4164
	ds_write_b32 v226, v152 offset:4168
	ds_write_b32 v226, v153 offset:4172
	ds_write_b32 v226, v154 offset:8320
	ds_write_b32 v226, v155 offset:8324
	ds_write_b32 v226, v156 offset:8328
	ds_write_b32 v226, v157 offset:8332
	ds_write_b32 v226, v158 offset:12480
	ds_write_b32 v226, v159 offset:12484
	ds_write_b32 v226, v160 offset:12488
	ds_write_b32 v226, v161 offset:12492
	v_mad_u32_u24 v232, v235, s35, v236
	s_waitcnt lgkmcnt(0)
	s_barrier
	ds_read2_b32 v[146:147], v227 offset1:65
	ds_read2_b32 v[148:149], v227 offset0:130 offset1:195
	ds_read2_b32 v[150:151], v228 offset0:4 offset1:69
	ds_read2_b32 v[152:153], v228 offset0:134 offset1:199
	ds_read2_b32 v[154:155], v229 offset1:65
	ds_read2_b32 v[156:157], v229 offset0:130 offset1:195
	ds_read2_b32 v[158:159], v230 offset0:4 offset1:69
	ds_read2_b32 v[160:161], v230 offset0:134 offset1:199
	s_add_u32 s26, s20, s32
	s_addc_u32 s27, s21, 0
	s_waitcnt lgkmcnt(0)
	s_barrier
	v_cvt_pk_bf16_f32 v146, v146, v147
	v_cvt_pk_bf16_f32 v147, v148, v149
	v_cvt_pk_bf16_f32 v148, v150, v151
	v_cvt_pk_bf16_f32 v149, v152, v153
	v_cvt_pk_bf16_f32 v154, v154, v155
	v_cvt_pk_bf16_f32 v155, v156, v157
	v_cvt_pk_bf16_f32 v156, v158, v159
	v_cvt_pk_bf16_f32 v157, v160, v161
	global_store_dwordx4 v232, v[146:149], s[20:21]
	global_store_dwordx4 v232, v[154:157], s[26:27]
	s_branch .Lwcm0_done
.Lwcm0_tail2:
	s_waitcnt vmcnt(0)
	v_readlane_b32 s20, v237, 8
	v_readlane_b32 s21, v237, 9
	v_readlane_b32 s32, v237, 10
	v_readlane_b32 s35, v237, 11
	ds_write_b32 v226, v146 offset:0
	ds_write_b32 v226, v147 offset:4
	ds_write_b32 v226, v148 offset:8
	ds_write_b32 v226, v149 offset:12
	ds_write_b32 v226, v150 offset:4160
	ds_write_b32 v226, v151 offset:4164
	ds_write_b32 v226, v152 offset:4168
	ds_write_b32 v226, v153 offset:4172
	ds_write_b32 v226, v154 offset:8320
	ds_write_b32 v226, v155 offset:8324
	ds_write_b32 v226, v156 offset:8328
	ds_write_b32 v226, v157 offset:8332
	ds_write_b32 v226, v158 offset:12480
	ds_write_b32 v226, v159 offset:12484
	ds_write_b32 v226, v160 offset:12488
	ds_write_b32 v226, v161 offset:12492
	v_mad_u32_u24 v232, v235, s35, v236
	s_waitcnt lgkmcnt(0)
	s_barrier
	ds_read2_b32 v[146:147], v227 offset1:65
	ds_read2_b32 v[148:149], v227 offset0:130 offset1:195
	ds_read2_b32 v[150:151], v228 offset0:4 offset1:69
	ds_read2_b32 v[152:153], v228 offset0:134 offset1:199
	ds_read2_b32 v[154:155], v229 offset1:65
	ds_read2_b32 v[156:157], v229 offset0:130 offset1:195
	ds_read2_b32 v[158:159], v230 offset0:4 offset1:69
	ds_read2_b32 v[160:161], v230 offset0:134 offset1:199
	s_add_u32 s26, s20, s32
	s_addc_u32 s27, s21, 0
	s_waitcnt lgkmcnt(0)
	s_barrier
	v_cvt_pk_bf16_f32 v146, v146, v147
	v_cvt_pk_bf16_f32 v147, v148, v149
	v_cvt_pk_bf16_f32 v148, v150, v151
	v_cvt_pk_bf16_f32 v149, v152, v153
	v_cvt_pk_bf16_f32 v154, v154, v155
	v_cvt_pk_bf16_f32 v155, v156, v157
	v_cvt_pk_bf16_f32 v156, v158, v159
	v_cvt_pk_bf16_f32 v157, v160, v161
	global_store_dwordx4 v232, v[146:149], s[20:21]
	global_store_dwordx4 v232, v[154:157], s[26:27]
	v_readlane_b32 s20, v237, 12
	v_readlane_b32 s21, v237, 13
	v_readlane_b32 s32, v237, 14
	v_readlane_b32 s35, v237, 15
	ds_write_b32 v226, v162 offset:0
	ds_write_b32 v226, v163 offset:4
	ds_write_b32 v226, v164 offset:8
	ds_write_b32 v226, v165 offset:12
	ds_write_b32 v226, v166 offset:4160
	ds_write_b32 v226, v167 offset:4164
	ds_write_b32 v226, v168 offset:4168
	ds_write_b32 v226, v169 offset:4172
	ds_write_b32 v226, v170 offset:8320
	ds_write_b32 v226, v171 offset:8324
	ds_write_b32 v226, v172 offset:8328
	ds_write_b32 v226, v173 offset:8332
	ds_write_b32 v226, v174 offset:12480
	ds_write_b32 v226, v175 offset:12484
	ds_write_b32 v226, v176 offset:12488
	ds_write_b32 v226, v177 offset:12492
	v_mad_u32_u24 v232, v235, s35, v236
	s_waitcnt lgkmcnt(0)
	s_barrier
	ds_read2_b32 v[162:163], v227 offset1:65
	ds_read2_b32 v[164:165], v227 offset0:130 offset1:195
	ds_read2_b32 v[166:167], v228 offset0:4 offset1:69
	ds_read2_b32 v[168:169], v228 offset0:134 offset1:199
	ds_read2_b32 v[170:171], v229 offset1:65
	ds_read2_b32 v[172:173], v229 offset0:130 offset1:195
	ds_read2_b32 v[174:175], v230 offset0:4 offset1:69
	ds_read2_b32 v[176:177], v230 offset0:134 offset1:199
	s_add_u32 s26, s20, s32
	s_addc_u32 s27, s21, 0
	s_waitcnt lgkmcnt(0)
	s_barrier
	v_cvt_pk_bf16_f32 v162, v162, v163
	v_cvt_pk_bf16_f32 v163, v164, v165
	v_cvt_pk_bf16_f32 v164, v166, v167
	v_cvt_pk_bf16_f32 v165, v168, v169
	v_cvt_pk_bf16_f32 v170, v170, v171
	v_cvt_pk_bf16_f32 v171, v172, v173
	v_cvt_pk_bf16_f32 v172, v174, v175
	v_cvt_pk_bf16_f32 v173, v176, v177
	global_store_dwordx4 v232, v[162:165], s[20:21]
	global_store_dwordx4 v232, v[170:173], s[26:27]
	s_branch .Lwcm0_done
.Lwcm0_p2:
	s_waitcnt vmcnt(0)
	v_readlane_b32 s20, v237, 8
	v_readlane_b32 s21, v237, 9
	v_readlane_b32 s32, v237, 10
	v_readlane_b32 s35, v237, 11
	ds_write_b32 v226, v146 offset:0
	ds_write_b32 v226, v147 offset:4
	ds_write_b32 v226, v148 offset:8
	ds_write_b32 v226, v149 offset:12
	ds_write_b32 v226, v150 offset:4160
	ds_write_b32 v226, v151 offset:4164
	ds_write_b32 v226, v152 offset:4168
	ds_write_b32 v226, v153 offset:4172
	ds_write_b32 v226, v154 offset:8320
	ds_write_b32 v226, v155 offset:8324
	ds_write_b32 v226, v156 offset:8328
	ds_write_b32 v226, v157 offset:8332
	ds_write_b32 v226, v158 offset:12480
	ds_write_b32 v226, v159 offset:12484
	ds_write_b32 v226, v160 offset:12488
	ds_write_b32 v226, v161 offset:12492
	v_mad_u32_u24 v232, v235, s35, v236
	s_waitcnt lgkmcnt(0)
	s_barrier
	ds_read2_b32 v[146:147], v227 offset1:65
	ds_read2_b32 v[148:149], v227 offset0:130 offset1:195
	ds_read2_b32 v[150:151], v228 offset0:4 offset1:69
	ds_read2_b32 v[152:153], v228 offset0:134 offset1:199
	ds_read2_b32 v[154:155], v229 offset1:65
	ds_read2_b32 v[156:157], v229 offset0:130 offset1:195
	ds_read2_b32 v[158:159], v230 offset0:4 offset1:69
	ds_read2_b32 v[160:161], v230 offset0:134 offset1:199
	s_add_u32 s26, s20, s32
	s_addc_u32 s27, s21, 0
	s_waitcnt lgkmcnt(0)
	s_barrier
	v_cvt_pk_bf16_f32 v146, v146, v147
	v_cvt_pk_bf16_f32 v147, v148, v149
	v_cvt_pk_bf16_f32 v148, v150, v151
	v_cvt_pk_bf16_f32 v149, v152, v153
	v_cvt_pk_bf16_f32 v154, v154, v155
	v_cvt_pk_bf16_f32 v155, v156, v157
	v_cvt_pk_bf16_f32 v156, v158, v159
	v_cvt_pk_bf16_f32 v157, v160, v161
	global_store_dwordx4 v232, v[146:149], s[20:21]
	global_store_dwordx4 v232, v[154:157], s[26:27]
	v_readlane_b32 s20, v237, 12
	v_readlane_b32 s21, v237, 13
	v_readlane_b32 s32, v237, 14
	v_readlane_b32 s35, v237, 15
	ds_write_b32 v226, v162 offset:0
	ds_write_b32 v226, v163 offset:4
	ds_write_b32 v226, v164 offset:8
	ds_write_b32 v226, v165 offset:12
	ds_write_b32 v226, v166 offset:4160
	ds_write_b32 v226, v167 offset:4164
	ds_write_b32 v226, v168 offset:4168
	ds_write_b32 v226, v169 offset:4172
	ds_write_b32 v226, v170 offset:8320
	ds_write_b32 v226, v171 offset:8324
	ds_write_b32 v226, v172 offset:8328
	ds_write_b32 v226, v173 offset:8332
	ds_write_b32 v226, v174 offset:12480
	ds_write_b32 v226, v175 offset:12484
	ds_write_b32 v226, v176 offset:12488
	ds_write_b32 v226, v177 offset:12492
	v_mad_u32_u24 v232, v235, s35, v236
	s_waitcnt lgkmcnt(0)
	s_barrier
	ds_read2_b32 v[162:163], v227 offset1:65
	ds_read2_b32 v[164:165], v227 offset0:130 offset1:195
	ds_read2_b32 v[166:167], v228 offset0:4 offset1:69
	ds_read2_b32 v[168:169], v228 offset0:134 offset1:199
	ds_read2_b32 v[170:171], v229 offset1:65
	ds_read2_b32 v[172:173], v229 offset0:130 offset1:195
	ds_read2_b32 v[174:175], v230 offset0:4 offset1:69
	ds_read2_b32 v[176:177], v230 offset0:134 offset1:199
	s_add_u32 s26, s20, s32
	s_addc_u32 s27, s21, 0
	s_waitcnt lgkmcnt(0)
	s_barrier
	v_cvt_pk_bf16_f32 v162, v162, v163
	v_cvt_pk_bf16_f32 v163, v164, v165
	v_cvt_pk_bf16_f32 v164, v166, v167
	v_cvt_pk_bf16_f32 v165, v168, v169
	v_cvt_pk_bf16_f32 v170, v170, v171
	v_cvt_pk_bf16_f32 v171, v172, v173
	v_cvt_pk_bf16_f32 v172, v174, v175
	v_cvt_pk_bf16_f32 v173, v176, v177
	global_store_dwordx4 v232, v[162:165], s[20:21]
	global_store_dwordx4 v232, v[170:173], s[26:27]
	s_branch .Lwcm0_done

.Lwcm1_loop:
	s_waitcnt vmcnt(8)
	v_readlane_b32 s20, v237, 8
	v_readlane_b32 s21, v237, 9
	v_readlane_b32 s32, v237, 10
	v_readlane_b32 s35, v237, 11
	ds_write_b32 v226, v146 offset:0
	ds_write_b32 v226, v147 offset:4
	ds_write_b32 v226, v148 offset:8
	ds_write_b32 v226, v149 offset:12
	ds_write_b32 v226, v150 offset:4160
	ds_write_b32 v226, v151 offset:4164
	ds_write_b32 v226, v152 offset:4168
	ds_write_b32 v226, v153 offset:4172
	ds_write_b32 v226, v154 offset:8320
	ds_write_b32 v226, v155 offset:8324
	ds_write_b32 v226, v156 offset:8328
	ds_write_b32 v226, v157 offset:8332
	ds_write_b32 v226, v158 offset:12480
	ds_write_b32 v226, v159 offset:12484
	ds_write_b32 v226, v160 offset:12488
	ds_write_b32 v226, v161 offset:12492
	v_mad_u32_u24 v232, v235, s35, v236
	s_waitcnt lgkmcnt(0)
	s_barrier
	ds_read2_b32 v[146:147], v227 offset1:65
	ds_read2_b32 v[148:149], v227 offset0:130 offset1:195
	ds_read2_b32 v[150:151], v228 offset0:4 offset1:69
	ds_read2_b32 v[152:153], v228 offset0:134 offset1:199
	ds_read2_b32 v[154:155], v229 offset1:65
	ds_read2_b32 v[156:157], v229 offset0:130 offset1:195
	ds_read2_b32 v[158:159], v230 offset0:4 offset1:69
	ds_read2_b32 v[160:161], v230 offset0:134 offset1:199
	s_add_u32 s26, s20, s32
	s_addc_u32 s27, s21, 0
	s_waitcnt lgkmcnt(0)
	s_barrier
	v_cvt_pk_bf16_f32 v146, v146, v147
	v_cvt_pk_bf16_f32 v147, v148, v149
	v_cvt_pk_bf16_f32 v148, v150, v151
	v_cvt_pk_bf16_f32 v149, v152, v153
	v_cvt_pk_bf16_f32 v154, v154, v155
	v_cvt_pk_bf16_f32 v155, v156, v157
	v_cvt_pk_bf16_f32 v156, v158, v159
	v_cvt_pk_bf16_f32 v157, v160, v161
	global_store_dwordx4 v232, v[146:149], s[20:21]
	global_store_dwordx4 v232, v[154:157], s[26:27]
	s_cmp_ge_u32 s100, s22
	s_cbranch_scc1 .Lwcm1_tail0
	s_cmpk_ge_u32 s100, 0x900
	s_cbranch_scc1 .Lwcm1_t3_4
	s_cmpk_ge_u32 s100, 0x380
	s_cbranch_scc1 .Lwcm1_t2_4
	s_cmpk_ge_u32 s100, 0x280
	s_cbranch_scc1 .Lwcm1_t1_4
	s_movk_i32 s14, 0x78
	s_sub_u32 s99, s100, 0
	s_mul_i32 s44, s99, 0x66667
	s_lshr_b32 s44, s44, 24
	s_mul_i32 s36, s44, 40
	s_sub_u32 s99, s99, s36
	s_mul_i32 s38, s44, 0xa0000
	s_lshl_b32 s36, s99, 8
	s_add_u32 s38, s38, s36
	s_add_u32 s38, s38, 0xa00000
	s_lshl_b32 s36, s99, 6
	s_mov_b32 s32, 0x10000
	s_mul_i32 s36, s36, 0x800
	s_lshl_b32 s44, s44, 7
	s_add_u32 s36, s36, s44
	s_add_u32 s36, s36, 0x500000
	s_mov_b32 s37, 0x28000
	s_movk_i32 s44, 0x800
	s_mov_b32 s99, 0x2800
	s_branch .Lwcm1_tj_4

.Lwcm1_tj_4:
	s_load_dwordx2 s[8:9], s[0:1], s14
	s_add_u32 s20, s12, s36
	s_addc_u32 s21, s13, 0
	v_mad_u32_u24 v231, v233, s99, v234
	v_writelane_b32 v237, s20, 8
	v_writelane_b32 v237, s21, 9
	v_writelane_b32 v237, s32, 10
	v_writelane_b32 v237, s44, 11
	s_add_u32 s100, s100, s23
	s_waitcnt lgkmcnt(0)
	s_add_u32 s38, s8, s38
	s_addc_u32 s39, s9, 0
	global_load_dwordx4 v[146:149], v231, s[38:39]
	s_add_u32 s38, s38, s37
	s_addc_u32 s39, s39, 0
	global_load_dwordx4 v[150:153], v231, s[38:39]
	s_add_u32 s38, s38, s37
	s_addc_u32 s39, s39, 0
	global_load_dwordx4 v[154:157], v231, s[38:39]
	s_add_u32 s38, s38, s37
	s_addc_u32 s39, s39, 0
	global_load_dwordx4 v[158:161], v231, s[38:39]
	s_waitcnt vmcnt(8)
	v_readlane_b32 s20, v237, 12
	v_readlane_b32 s21, v237, 13
	v_readlane_b32 s32, v237, 14
	v_readlane_b32 s35, v237, 15
	ds_write_b32 v226, v162 offset:0
	ds_write_b32 v226, v163 offset:4
	ds_write_b32 v226, v164 offset:8
	ds_write_b32 v226, v165 offset:12
	ds_write_b32 v226, v166 offset:4160
	ds_write_b32 v226, v167 offset:4164
	ds_write_b32 v226, v168 offset:4168
	ds_write_b32 v226, v169 offset:4172
	ds_write_b32 v226, v170 offset:8320
	ds_write_b32 v226, v171 offset:8324
	ds_write_b32 v226, v172 offset:8328
	ds_write_b32 v226, v173 offset:8332
	ds_write_b32 v226, v174 offset:12480
	ds_write_b32 v226, v175 offset:12484
	ds_write_b32 v226, v176 offset:12488
	ds_write_b32 v226, v177 offset:12492
	v_mad_u32_u24 v232, v235, s35, v236
	s_waitcnt lgkmcnt(0)
	s_barrier
	ds_read2_b32 v[162:163], v227 offset1:65
	ds_read2_b32 v[164:165], v227 offset0:130 offset1:195
	ds_read2_b32 v[166:167], v228 offset0:4 offset1:69
	ds_read2_b32 v[168:169], v228 offset0:134 offset1:199
	ds_read2_b32 v[170:171], v229 offset1:65
	ds_read2_b32 v[172:173], v229 offset0:130 offset1:195
	ds_read2_b32 v[174:175], v230 offset0:4 offset1:69
	ds_read2_b32 v[176:177], v230 offset0:134 offset1:199
	s_add_u32 s26, s20, s32
	s_addc_u32 s27, s21, 0
	s_waitcnt lgkmcnt(0)
	s_barrier
	v_cvt_pk_bf16_f32 v162, v162, v163
	v_cvt_pk_bf16_f32 v163, v164, v165
	v_cvt_pk_bf16_f32 v164, v166, v167
	v_cvt_pk_bf16_f32 v165, v168, v169
	v_cvt_pk_bf16_f32 v170, v170, v171
	v_cvt_pk_bf16_f32 v171, v172, v173
	v_cvt_pk_bf16_f32 v172, v174, v175
	v_cvt_pk_bf16_f32 v173, v176, v177
	global_store_dwordx4 v232, v[162:165], s[20:21]
	global_store_dwordx4 v232, v[170:173], s[26:27]
	s_cmp_ge_u32 s100, s22
	s_cbranch_scc1 .Lwcm1_tail1
	s_cmpk_ge_u32 s100, 0x900
	s_cbranch_scc1 .Lwcm1_t3_5
	s_cmpk_ge_u32 s100, 0x380
	s_cbranch_scc1 .Lwcm1_t2_5
	s_cmpk_ge_u32 s100, 0x280
	s_cbranch_scc1 .Lwcm1_t1_5
	s_movk_i32 s14, 0x78
	s_sub_u32 s99, s100, 0
	s_mul_i32 s44, s99, 0x66667
	s_lshr_b32 s44, s44, 24
	s_mul_i32 s36, s44, 40
	s_sub_u32 s99, s99, s36
	s_mul_i32 s38, s44, 0xa0000
	s_lshl_b32 s36, s99, 8
	s_add_u32 s38, s38, s36
	s_add_u32 s38, s38, 0xa00000
	s_lshl_b32 s36, s99, 6
	s_mov_b32 s32, 0x10000
	s_mul_i32 s36, s36, 0x800
	s_lshl_b32 s44, s44, 7
	s_add_u32 s36, s36, s44
	s_add_u32 s36, s36, 0x500000
	s_mov_b32 s37, 0x28000
	s_movk_i32 s44, 0x800
	s_mov_b32 s99, 0x2800
	s_branch .Lwcm1_tj_5

.Lwcm1_tj_5:
	s_load_dwordx2 s[8:9], s[0:1], s14
	s_add_u32 s20, s12, s36
	s_addc_u32 s21, s13, 0
	v_mad_u32_u24 v231, v233, s99, v234
	v_writelane_b32 v237, s20, 12
	v_writelane_b32 v237, s21, 13
	v_writelane_b32 v237, s32, 14
	v_writelane_b32 v237, s44, 15
	s_add_u32 s100, s100, s23
	s_waitcnt lgkmcnt(0)
	s_add_u32 s38, s8, s38
	s_addc_u32 s39, s9, 0
	global_load_dwordx4 v[162:165], v231, s[38:39]
	s_add_u32 s38, s38, s37
	s_addc_u32 s39, s39, 0
	global_load_dwordx4 v[166:169], v231, s[38:39]
	s_add_u32 s38, s38, s37
	s_addc_u32 s39, s39, 0
	global_load_dwordx4 v[170:173], v231, s[38:39]
	s_add_u32 s38, s38, s37
	s_addc_u32 s39, s39, 0
	global_load_dwordx4 v[174:177], v231, s[38:39]
	s_waitcnt vmcnt(8)
	v_readlane_b32 s20, v237, 16
	v_readlane_b32 s21, v237, 17
	v_readlane_b32 s32, v237, 18
	v_readlane_b32 s35, v237, 19
	ds_write_b32 v226, v178 offset:0
	ds_write_b32 v226, v179 offset:4
	ds_write_b32 v226, v180 offset:8
	ds_write_b32 v226, v181 offset:12
	ds_write_b32 v226, v182 offset:4160
	ds_write_b32 v226, v183 offset:4164
	ds_write_b32 v226, v184 offset:4168
	ds_write_b32 v226, v185 offset:4172
	ds_write_b32 v226, v186 offset:8320
	ds_write_b32 v226, v187 offset:8324
	ds_write_b32 v226, v188 offset:8328
	ds_write_b32 v226, v189 offset:8332
	ds_write_b32 v226, v190 offset:12480
	ds_write_b32 v226, v191 offset:12484
	ds_write_b32 v226, v192 offset:12488
	ds_write_b32 v226, v193 offset:12492
	v_mad_u32_u24 v232, v235, s35, v236
	s_waitcnt lgkmcnt(0)
	s_barrier
	ds_read2_b32 v[178:179], v227 offset1:65
	ds_read2_b32 v[180:181], v227 offset0:130 offset1:195
	ds_read2_b32 v[182:183], v228 offset0:4 offset1:69
	ds_read2_b32 v[184:185], v228 offset0:134 offset1:199
	ds_read2_b32 v[186:187], v229 offset1:65
	ds_read2_b32 v[188:189], v229 offset0:130 offset1:195
	ds_read2_b32 v[190:191], v230 offset0:4 offset1:69
	ds_read2_b32 v[192:193], v230 offset0:134 offset1:199
	s_add_u32 s26, s20, s32
	s_addc_u32 s27, s21, 0
	s_waitcnt lgkmcnt(0)
	s_barrier
	v_cvt_pk_bf16_f32 v178, v178, v179
	v_cvt_pk_bf16_f32 v179, v180, v181
	v_cvt_pk_bf16_f32 v180, v182, v183
	v_cvt_pk_bf16_f32 v181, v184, v185
	v_cvt_pk_bf16_f32 v186, v186, v187
	v_cvt_pk_bf16_f32 v187, v188, v189
	v_cvt_pk_bf16_f32 v188, v190, v191
	v_cvt_pk_bf16_f32 v189, v192, v193
	global_store_dwordx4 v232, v[178:181], s[20:21]
	global_store_dwordx4 v232, v[186:189], s[26:27]
	s_cmp_ge_u32 s100, s22
	s_cbranch_scc1 .Lwcm1_tail2
	s_cmpk_ge_u32 s100, 0x900
	s_cbranch_scc1 .Lwcm1_t3_6
	s_cmpk_ge_u32 s100, 0x380
	s_cbranch_scc1 .Lwcm1_t2_6
	s_cmpk_ge_u32 s100, 0x280
	s_cbranch_scc1 .Lwcm1_t1_6
	s_movk_i32 s14, 0x78
	s_sub_u32 s99, s100, 0
	s_mul_i32 s44, s99, 0x66667
	s_lshr_b32 s44, s44, 24
	s_mul_i32 s36, s44, 40
	s_sub_u32 s99, s99, s36
	s_mul_i32 s38, s44, 0xa0000
	s_lshl_b32 s36, s99, 8
	s_add_u32 s38, s38, s36
	s_add_u32 s38, s38, 0xa00000
	s_lshl_b32 s36, s99, 6
	s_mov_b32 s32, 0x10000
	s_mul_i32 s36, s36, 0x800
	s_lshl_b32 s44, s44, 7
	s_add_u32 s36, s36, s44
	s_add_u32 s36, s36, 0x500000
	s_mov_b32 s37, 0x28000
	s_movk_i32 s44, 0x800
	s_mov_b32 s99, 0x2800
	s_branch .Lwcm1_tj_6

.Lwcm1_tail2:
	s_waitcnt vmcnt(0)
	v_readlane_b32 s20, v237, 8
	v_readlane_b32 s21, v237, 9
	v_readlane_b32 s32, v237, 10
	v_readlane_b32 s35, v237, 11
	ds_write_b32 v226, v146 offset:0
	ds_write_b32 v226, v147 offset:4
	ds_write_b32 v226, v148 offset:8
	ds_write_b32 v226, v149 offset:12
	ds_write_b32 v226, v150 offset:4160
	ds_write_b32 v226, v151 offset:4164
	ds_write_b32 v226, v152 offset:4168
	ds_write_b32 v226, v153 offset:4172
	ds_write_b32 v226, v154 offset:8320
	ds_write_b32 v226, v155 offset:8324
	ds_write_b32 v226, v156 offset:8328
	ds_write_b32 v226, v157 offset:8332
	ds_write_b32 v226, v158 offset:12480
	ds_write_b32 v226, v159 offset:12484
	ds_write_b32 v226, v160 offset:12488
	ds_write_b32 v226, v161 offset:12492
	v_mad_u32_u24 v232, v235, s35, v236
	s_waitcnt lgkmcnt(0)
	s_barrier
	ds_read2_b32 v[146:147], v227 offset1:65
	ds_read2_b32 v[148:149], v227 offset0:130 offset1:195
	ds_read2_b32 v[150:151], v228 offset0:4 offset1:69
	ds_read2_b32 v[152:153], v228 offset0:134 offset1:199
	ds_read2_b32 v[154:155], v229 offset1:65
	ds_read2_b32 v[156:157], v229 offset0:130 offset1:195
	ds_read2_b32 v[158:159], v230 offset0:4 offset1:69
	ds_read2_b32 v[160:161], v230 offset0:134 offset1:199
	s_add_u32 s26, s20, s32
	s_addc_u32 s27, s21, 0
	s_waitcnt lgkmcnt(0)
	s_barrier
	v_cvt_pk_bf16_f32 v146, v146, v147
	v_cvt_pk_bf16_f32 v147, v148, v149
	v_cvt_pk_bf16_f32 v148, v150, v151
	v_cvt_pk_bf16_f32 v149, v152, v153
	v_cvt_pk_bf16_f32 v154, v154, v155
	v_cvt_pk_bf16_f32 v155, v156, v157
	v_cvt_pk_bf16_f32 v156, v158, v159
	v_cvt_pk_bf16_f32 v157, v160, v161
	global_store_dwordx4 v232, v[146:149], s[20:21]
	global_store_dwordx4 v232, v[154:157], s[26:27]
	v_readlane_b32 s20, v237, 12
	v_readlane_b32 s21, v237, 13
	v_readlane_b32 s32, v237, 14
	v_readlane_b32 s35, v237, 15
	ds_write_b32 v226, v162 offset:0
	ds_write_b32 v226, v163 offset:4
	ds_write_b32 v226, v164 offset:8
	ds_write_b32 v226, v165 offset:12
	ds_write_b32 v226, v166 offset:4160
	ds_write_b32 v226, v167 offset:4164
	ds_write_b32 v226, v168 offset:4168
	ds_write_b32 v226, v169 offset:4172
	ds_write_b32 v226, v170 offset:8320
	ds_write_b32 v226, v171 offset:8324
	ds_write_b32 v226, v172 offset:8328
	ds_write_b32 v226, v173 offset:8332
	ds_write_b32 v226, v174 offset:12480
	ds_write_b32 v226, v175 offset:12484
	ds_write_b32 v226, v176 offset:12488
	ds_write_b32 v226, v177 offset:12492
	v_mad_u32_u24 v232, v235, s35, v236
	s_waitcnt lgkmcnt(0)
	s_barrier
	ds_read2_b32 v[162:163], v227 offset1:65
	ds_read2_b32 v[164:165], v227 offset0:130 offset1:195
	ds_read2_b32 v[166:167], v228 offset0:4 offset1:69
	ds_read2_b32 v[168:169], v228 offset0:134 offset1:199
	ds_read2_b32 v[170:171], v229 offset1:65
	ds_read2_b32 v[172:173], v229 offset0:130 offset1:195
	ds_read2_b32 v[174:175], v230 offset0:4 offset1:69
	ds_read2_b32 v[176:177], v230 offset0:134 offset1:199
	s_add_u32 s26, s20, s32
	s_addc_u32 s27, s21, 0
	s_waitcnt lgkmcnt(0)
	s_barrier
	v_cvt_pk_bf16_f32 v162, v162, v163
	v_cvt_pk_bf16_f32 v163, v164, v165
	v_cvt_pk_bf16_f32 v164, v166, v167
	v_cvt_pk_bf16_f32 v165, v168, v169
	v_cvt_pk_bf16_f32 v170, v170, v171
	v_cvt_pk_bf16_f32 v171, v172, v173
	v_cvt_pk_bf16_f32 v172, v174, v175
	v_cvt_pk_bf16_f32 v173, v176, v177
	global_store_dwordx4 v232, v[162:165], s[20:21]
	global_store_dwordx4 v232, v[170:173], s[26:27]
	s_branch .Lwcm1_done
.Lwcm1_p2:
	s_waitcnt vmcnt(0)
	v_readlane_b32 s20, v237, 8
	v_readlane_b32 s21, v237, 9
	v_readlane_b32 s32, v237, 10
	v_readlane_b32 s35, v237, 11
	ds_write_b32 v226, v146 offset:0
	ds_write_b32 v226, v147 offset:4
	ds_write_b32 v226, v148 offset:8
	ds_write_b32 v226, v149 offset:12
	ds_write_b32 v226, v150 offset:4160
	ds_write_b32 v226, v151 offset:4164
	ds_write_b32 v226, v152 offset:4168
	ds_write_b32 v226, v153 offset:4172
	ds_write_b32 v226, v154 offset:8320
	ds_write_b32 v226, v155 offset:8324
	ds_write_b32 v226, v156 offset:8328
	ds_write_b32 v226, v157 offset:8332
	ds_write_b32 v226, v158 offset:12480
	ds_write_b32 v226, v159 offset:12484
	ds_write_b32 v226, v160 offset:12488
	ds_write_b32 v226, v161 offset:12492
	v_mad_u32_u24 v232, v235, s35, v236
	s_waitcnt lgkmcnt(0)
	s_barrier
	ds_read2_b32 v[146:147], v227 offset1:65
	ds_read2_b32 v[148:149], v227 offset0:130 offset1:195
	ds_read2_b32 v[150:151], v228 offset0:4 offset1:69
	ds_read2_b32 v[152:153], v228 offset0:134 offset1:199
	ds_read2_b32 v[154:155], v229 offset1:65
	ds_read2_b32 v[156:157], v229 offset0:130 offset1:195
	ds_read2_b32 v[158:159], v230 offset0:4 offset1:69
	ds_read2_b32 v[160:161], v230 offset0:134 offset1:199
	s_add_u32 s26, s20, s32
	s_addc_u32 s27, s21, 0
	s_waitcnt lgkmcnt(0)
	s_barrier
	v_cvt_pk_bf16_f32 v146, v146, v147
	v_cvt_pk_bf16_f32 v147, v148, v149
	v_cvt_pk_bf16_f32 v148, v150, v151
	v_cvt_pk_bf16_f32 v149, v152, v153
	v_cvt_pk_bf16_f32 v154, v154, v155
	v_cvt_pk_bf16_f32 v155, v156, v157
	v_cvt_pk_bf16_f32 v156, v158, v159
	v_cvt_pk_bf16_f32 v157, v160, v161
	global_store_dwordx4 v232, v[146:149], s[20:21]
	global_store_dwordx4 v232, v[154:157], s[26:27]
	v_readlane_b32 s20, v237, 12
	v_readlane_b32 s21, v237, 13
	v_readlane_b32 s32, v237, 14
	v_readlane_b32 s35, v237, 15
	ds_write_b32 v226, v162 offset:0
	ds_write_b32 v226, v163 offset:4
	ds_write_b32 v226, v164 offset:8
	ds_write_b32 v226, v165 offset:12
	ds_write_b32 v226, v166 offset:4160
	ds_write_b32 v226, v167 offset:4164
	ds_write_b32 v226, v168 offset:4168
	ds_write_b32 v226, v169 offset:4172
	ds_write_b32 v226, v170 offset:8320
	ds_write_b32 v226, v171 offset:8324
	ds_write_b32 v226, v172 offset:8328
	ds_write_b32 v226, v173 offset:8332
	ds_write_b32 v226, v174 offset:12480
	ds_write_b32 v226, v175 offset:12484
	ds_write_b32 v226, v176 offset:12488
	ds_write_b32 v226, v177 offset:12492
	v_mad_u32_u24 v232, v235, s35, v236
	s_waitcnt lgkmcnt(0)
	s_barrier
	ds_read2_b32 v[162:163], v227 offset1:65
	ds_read2_b32 v[164:165], v227 offset0:130 offset1:195
	ds_read2_b32 v[166:167], v228 offset0:4 offset1:69
	ds_read2_b32 v[168:169], v228 offset0:134 offset1:199
	ds_read2_b32 v[170:171], v229 offset1:65
	ds_read2_b32 v[172:173], v229 offset0:130 offset1:195
	ds_read2_b32 v[174:175], v230 offset0:4 offset1:69
	ds_read2_b32 v[176:177], v230 offset0:134 offset1:199
	s_add_u32 s26, s20, s32
	s_addc_u32 s27, s21, 0
	s_waitcnt lgkmcnt(0)
	s_barrier
	v_cvt_pk_bf16_f32 v162, v162, v163
	v_cvt_pk_bf16_f32 v163, v164, v165
	v_cvt_pk_bf16_f32 v164, v166, v167
	v_cvt_pk_bf16_f32 v165, v168, v169
	v_cvt_pk_bf16_f32 v170, v170, v171
	v_cvt_pk_bf16_f32 v171, v172, v173
	v_cvt_pk_bf16_f32 v172, v174, v175
	v_cvt_pk_bf16_f32 v173, v176, v177
	global_store_dwordx4 v232, v[162:165], s[20:21]
	global_store_dwordx4 v232, v[170:173], s[26:27]
	s_branch .Lwcm1_done
